# outproj layer 0: workgroups that own a context pair-item run it before their two 256x256 tiles (tile epilogues fall out of step with the other workgroups)
# speedup vs baseline: 1.0074x; 1.0029x over previous
; __global__ void __launch_bounds__(NTHR, 2) fwd_megakernel(Params p_byval) {
;   KP p = (KP)__builtin_amdgcn_kernarg_segment_ptr();
;   extern __shared__ __attribute__((aligned(16))) char lds[];
;   cg::grid_group grid = cg::this_grid();
;   uint4* xbw = (uint4*)(lds + LDS_MAIN);
;   if (threadIdx.x == 0) *xbw = make_uint4(0u, 0u, 0u, 0u);
;   __syncthreads();
_Z14fwd_megakernel6Params:
	s_mov_b32 s32, 0
	s_add_u32 s12, s0, 0xc8
	s_addc_u32 s13, s1, 0
	v_and_b32_e32 v196, 0x3ff, v0
	v_cmp_eq_u32_e64 s[6:7], 0, v196
	s_mov_b64 s[4:5], exec
	s_nop 0
	v_writelane_b32 v253, s6, 0
	s_nop 1
	v_writelane_b32 v253, s7, 1
	s_and_b64 s[6:7], s[4:5], s[6:7]
	s_mov_b64 exec, s[6:7]
	s_cbranch_execz .LBB0_2
	s_add_i32 s3, 0, 0x22000
	v_mov_b32_e32 v2, 0
	v_mov_b32_e32 v3, v2
	v_mov_b32_e32 v4, v2
	v_mov_b32_e32 v5, v2
	v_mov_b32_e32 v1, s3
	ds_write_b128 v1, v[2:5]

; DI int otid() { int t = threadIdx.x; asm volatile("" : "+v"(t)); return t; }
; DI void phase_outproj(KP p, int l, char* lds) {
;   unsigned char* ws = p->ws; asm volatile("" : "+s"(ws));
;   const bf16_t* Y = (const bf16_t*)(ws + WS_R1);
;   const bf16_t* wo = (const bf16_t*)(ws + WS_WOUT) + (size_t)l * 1024 * 1024;
;   const float* mod = (const float*)(ws + WS_MOD) + (size_t)l * 17 * 3072;
;   const float* xl = (l == 0) ? p->x : p->out;
;   float* ctx1 = (float*)(ws + WS_CTX1);
;   const int xcd = blockIdx.x & 7, lb = blockIdx.x >> 3, nlb = gridDim.x >> 3, hb = __builtin_amdgcn_readfirstlane(otid() >> 8);
;   const int nsm = (l == 0) ? 16 : 0;
;   for (int j = lb; j < 64; j += nlb) {
.LBB0_341:
	s_load_dwordx2 s[36:37], s[0:1], 0xb8
	v_readlane_b32 s18, v255, 26
	s_waitcnt lgkmcnt(0)
	s_add_u32 s34, s36, 0x18b5100
	v_readlane_b32 s19, v255, 27
	s_addc_u32 s35, s37, 0
	s_ashr_i32 s19, s18, 31
	s_lshl_b64 s[40:41], s[18:19], 21
	s_add_u32 s2, s36, s40
	s_addc_u32 s4, s37, s41
	s_add_u32 s52, s2, 0xc31100
	s_addc_u32 s53, s4, 0
	s_mov_b32 s4, s18
	v_writelane_b32 v255, s4, 26
	s_mul_hi_i32 s2, s18, 0x33000
	v_mov_b32_e32 v0, v196
	v_writelane_b32 v255, s5, 27
	s_mul_i32 s4, s18, 0x33000
	s_add_u32 s54, s36, s4
	v_readlane_b32 s4, v253, 2
	v_readlane_b32 s5, v253, 3
	s_addc_u32 s55, s37, s2
	s_add_i32 s2, s4, 5
	v_readlane_b32 s4, v253, 11
	s_cmp_lt_u32 s2, 13
	v_readlane_b32 s5, v253, 12
	s_cselect_b64 s[42:43], -1, 0
	s_andn2_b64 vcc, exec, s[4:5]
	v_readfirstlane_b32 s56, v0
	s_cmp_eq_u32 s32, 0
	s_cbranch_scc0 .Lop_after_ctx
	s_mov_b32 s32, 1
	s_branch .LBB0_354
.Lop_after_ctx:
	s_cbranch_vccnz .LBB0_354
	s_and_b64 s[4:5], s[42:43], exec
	s_cselect_b32 s2, 0, 0xb0
	s_add_u32 s4, s0, s2
	s_addc_u32 s5, s1, 0
	s_load_dwordx2 s[44:45], s[4:5], 0x0
	s_load_dwordx2 s[46:47], s[0:1], 0xb0
	v_readlane_b32 s57, v254, 43
	v_readlane_b32 s64, v254, 42

; DI void phase_outproj(KP p, int l, char* lds) {
;     ...
;   for (int j = lb; j < nsm; j += nlb) {
;     {
;       const int item = 2 * j + hb; const int bb = 2 * xcd + (item >> 4), m128 = (item >> 3) & 1, nt = item & 7;
;       const int m0 = (bb * 18 + 16 + m128) * 128, n0 = nt * 128;
;       const float* src = p->ctx + ((size_t)bb * CL + m128 * 128) * 1024;
;       float* dst = ctx1 + ((size_t)bb * CL + m128 * 128) * 1024;
;       const float* gt = mod + (size_t)16 * 3072 + 2048;
;       gemm_tile(Y + (size_t)m0 * 1024, 1024, wo + (size_t)n0 * 1024, 1024, 1024, lds, [&](int m, int n, f32x4 v) {
.LBB0_354:
	s_cmp_eq_u32 s32, 2
	s_cbranch_scc1 .LBB0_364
	v_readlane_b32 s4, v253, 13
	v_readlane_b32 s5, v253, 14
	s_and_b64 s[4:5], s[4:5], s[42:43]
	s_andn2_b64 vcc, exec, s[4:5]
	s_cbranch_vccnz .LBB0_363
	s_ashr_i32 s2, s56, 8
	s_add_u32 s18, s54, 0x32000
	s_addc_u32 s19, s55, 0
	s_add_u32 s20, s36, s40
	s_load_dwordx2 s[4:5], s[0:1], 0x10
	s_addc_u32 s21, s37, s41
	s_lshl_b32 s40, s2, 7
	v_readlane_b32 s41, v254, 43
	s_add_i32 s48, s41, s40
	v_readlane_b32 s40, v254, 40
	s_add_i32 s49, s40, s2
	s_add_u32 s40, s36, 0x1df85100
	s_addc_u32 s41, s37, 0
	v_readlane_b32 s50, v254, 42

; DI void phase_outproj(KP p, int l, char* lds) {
;     ...
;   for (int j = lb; j < nsm; j += nlb) {
;     {
;       const int item = 2 * j + hb; const int bb = 2 * xcd + (item >> 4), m128 = (item >> 3) & 1, nt = item & 7;
;       const int m0 = (bb * 18 + 16 + m128) * 128, n0 = nt * 128;
;       const float* src = p->ctx + ((size_t)bb * CL + m128 * 128) * 1024;
;       float* dst = ctx1 + ((size_t)bb * CL + m128 * 128) * 1024;
;       const float* gt = mod + (size_t)16 * 3072 + 2048;
;       gemm_tile(Y + (size_t)m0 * 1024, 1024, wo + (size_t)n0 * 1024, 1024, 1024, lds, [&](int m, int n, f32x4 v) {
;         const size_t o = (size_t)m * 1024 + n0 + n;
;         f32x4 xv = *(const f32x4*)(src + o), g = *(const f32x4*)(gt + n0 + n);
;         f32x4 r = {xv[0] + g[0] * v[0], xv[1] + g[1] * v[1], xv[2] + g[2] * v[2], xv[3] + g[3] * v[3]};
;         *(f32x4*)(dst + o) = r; });
;     }
;   }
.LBB0_363:
	s_cmp_eq_u32 s32, 1
	s_cbranch_scc0 .LBB0_364
	s_mov_b32 s32, 2
	s_branch .LBB0_341

; DI void xcd_barrier(const XcdBarrier& b) {
;   asm volatile("s_waitcnt vmcnt(0)" ::: "memory");
;   __syncthreads();
;   if (threadIdx.x == 0) {
;     unsigned* bar = b.bar;
;     __builtin_amdgcn_s_waitcnt(0);
;     unsigned nloc = b.st[0], nx = b.st[1];
;     if (nloc == 0u) { xcd_barrier_complete(bar, b.x, nloc, nx); b.st[0] = nloc; b.st[1] = nx; }
; __global__ void __launch_bounds__(NTHR, 2) fwd_megakernel(Params p_byval) {
;     ...
;   for (int ph = p->ph_lo; ph < p->ph_hi; ++ph) {
;     asm volatile("" : "+s"(p));
;     if (ph == 0) phase0(p, lds);
;     else {
;       const int l = (ph - 1) / 7, s = (ph - 1) % 7;
;       switch (s) {
;         case 0: phase_norm(p, l); break;
;         case 1: phase_inproj(p, l, lds); break;
;         case 2: phase_feat_a(p, l, lds); break;
;         case 3: phase_feat_b(p, l, lds); break;
;         case 4: phase_feat_c(p, l); break;
;         case 5: phase_mix(p, l, lds); break;
;         default: phase_outproj(p, l, lds); break;
;       }
;     }
;     if (ph + 1 < p->ph_hi) xcd_barrier(xb);
.LBB0_515:
	s_mov_b32 s32, 0
	s_load_dword s2, s[0:1], 0xc4
	v_readlane_b32 s4, v253, 2
	s_add_i32 s18, s4, 1
	v_readlane_b32 s5, v253, 3
	s_mov_b32 s4, s18
	v_writelane_b32 v253, s4, 2
	s_waitcnt lgkmcnt(0)
	s_cmp_ge_i32 s18, s2
	v_writelane_b32 v253, s5, 3
	s_mov_b64 s[4:5], -1
	s_cbranch_scc1 .LBB0_21
	s_waitcnt vmcnt(0)
	s_barrier
	s_mov_b64 s[4:5], exec
	v_readlane_b32 s18, v253, 0
	v_readlane_b32 s19, v253, 1
	s_and_b64 s[18:19], s[4:5], s[18:19]
	s_mov_b64 exec, s[18:19]
	s_cbranch_execz .LBB0_20
	v_readlane_b32 s2, v255, 23
	s_waitcnt vmcnt(0) expcnt(0) lgkmcnt(0)
	s_nop 0
	v_mov_b32_e32 v0, s2
	ds_read_b32 v3, v0
	v_readlane_b32 s2, v255, 24
	s_waitcnt lgkmcnt(0)
	v_cmp_ne_u32_e32 vcc, 0, v3
	v_mov_b32_e32 v0, s2
	ds_read_b32 v2, v0
	s_cbranch_vccnz .LBB0_532
	s_mov_b32 s2, 1
	s_branch .LBB0_520
